# attention fused QK/exp/PV block hand-pipelined: 4-deep LDS fragment prefetch, counted lgkmcnt, in-place exp
# speedup vs baseline: 1.0089x; 1.0089x over previous
; #define LAS __attribute__((address_space(3)))
; #define MFMA32(a, b, c) __builtin_amdgcn_mfma_f32_32x32x16_bf16((a), (b), (c), 0, 0, 0)
; DI int perm32k(int i) { return (i & 0x13) | ((i & 8) >> 1) | ((i & 4) << 1); }
; DI bf16x8 pack8(const f32x16& x, int s) { u32x4 p; p.x = pk2(x[8 * s], x[8 * s + 1]); p.y = pk2(x[8 * s + 2], x[8 * s + 3]); p.z = pk2(x[8 * s + 4], x[8 * s + 5]); p.w = pk2(x[8 * s + 6], x[8 * s + 7]); return __builtin_bit_cast(bf16x8, p); }
; DI void attn_unit(LAS unsigned char* lds, const bf16_t* __restrict__ Q, const bf16_t* __restrict__ Kg, const bf16_t* __restrict__ VT, bf16_t* __restrict__ MIX, int b, int h, int c0, int nq, int desc) {
;     ...
;       for (int i = 0; i < 16; ++i) { n0[i] = 0.f; n1[i] = 0.f; }
;       const LAS unsigned char* kb2 = lds + (buf ^ 1) * ATT_KB + perm32k(r31) * KROWB + 16 * hh;
;       __builtin_amdgcn_sched_barrier(0);
; #pragma unroll
;       for (int sx = 0; sx < 12; ++sx) { const bf16x8 a0 = *(const LAS bf16x8*)(kb2 + 32 * sx); const bf16x8 a1 = *(const LAS bf16x8*)(kb2 + 32 * KROWB + 32 * sx);
;         n0 = MFMA32(a0, qf[sx], n0); n1 = MFMA32(a1, qf[sx], n1);
; #pragma unroll
;         for (int j = 0; j < 3; ++j) { const int ei = 3 * sx + j; if (ei < 16) s0[ei] = __builtin_amdgcn_exp2f(s0[ei] - mrun); else if (ei < 32) s1[ei - 16] = __builtin_amdgcn_exp2f(s1[ei - 16] - mrun); }
;         __builtin_amdgcn_sched_barrier(0); }
;       float ps = 0.f;
; #pragma unroll
;       for (int i = 0; i < 16; ++i) ps += s0[i] + s1[i];
;       lrun += ps;
;       bf16x8 pf[4]; pf[0] = pack8(s0, 0); pf[1] = pack8(s0, 1); pf[2] = pack8(s1, 0); pf[3] = pack8(s1, 1);
.LBB0_551:
	s_xor_b32 s34, s12, 1
	s_mulk_i32 s34, 0x6400
	v_add_u32_e32 v223, s34, v208
	ds_read_b128 v[212:215], v223
	ds_read_b128 v[218:221], v223 offset:12800
	ds_read_b128 v[230:233], v223 offset:32
	ds_read_b128 v[234:237], v223 offset:12832
	v_sub_f32_e32 v82, v82, v211
	v_exp_f32_e32 v82, v82
	v_sub_f32_e32 v83, v83, v211
	v_exp_f32_e32 v83, v83
	v_sub_f32_e32 v84, v84, v211
	v_exp_f32_e32 v84, v84
	s_waitcnt lgkmcnt(3)
	v_mfma_f32_32x32x16_bf16 v[98:113], v[212:215], v[130:133], 0
	ds_read_b128 v[212:215], v223 offset:64
	v_sub_f32_e32 v85, v85, v211
	v_exp_f32_e32 v85, v85
	v_sub_f32_e32 v86, v86, v211
	v_exp_f32_e32 v86, v86
	s_waitcnt lgkmcnt(3)
	v_mfma_f32_32x32x16_bf16 v[114:129], v[218:221], v[130:133], 0
	ds_read_b128 v[218:221], v223 offset:12864
	v_sub_f32_e32 v87, v87, v211
	v_exp_f32_e32 v87, v87
	s_waitcnt lgkmcnt(3)
	v_mfma_f32_32x32x16_bf16 v[98:113], v[230:233], v[134:137], v[98:113]
	ds_read_b128 v[230:233], v223 offset:96
	v_sub_f32_e32 v88, v88, v211
	v_exp_f32_e32 v88, v88
	v_sub_f32_e32 v89, v89, v211
	v_exp_f32_e32 v89, v89
	s_waitcnt lgkmcnt(3)
	v_mfma_f32_32x32x16_bf16 v[114:129], v[234:237], v[134:137], v[114:129]
	ds_read_b128 v[234:237], v223 offset:12896
	v_sub_f32_e32 v90, v90, v211
	v_exp_f32_e32 v90, v90
	s_waitcnt lgkmcnt(3)
	v_mfma_f32_32x32x16_bf16 v[98:113], v[212:215], v[138:141], v[98:113]
	ds_read_b128 v[212:215], v223 offset:128
	v_sub_f32_e32 v91, v91, v211
	v_exp_f32_e32 v91, v91
	v_sub_f32_e32 v92, v92, v211
	v_exp_f32_e32 v92, v92
	s_waitcnt lgkmcnt(3)
	v_mfma_f32_32x32x16_bf16 v[114:129], v[218:221], v[138:141], v[114:129]
	ds_read_b128 v[218:221], v223 offset:12928
	v_sub_f32_e32 v93, v93, v211
	v_exp_f32_e32 v93, v93
	v_add_f32_e32 v238, v82, v86
	v_add_f32_e32 v239, v83, v87
	v_add_f32_e32 v240, v84, v88
	s_waitcnt lgkmcnt(3)
	v_mfma_f32_32x32x16_bf16 v[98:113], v[230:233], v[142:145], v[98:113]
	ds_read_b128 v[230:233], v223 offset:160
	v_sub_f32_e32 v94, v94, v211
	v_exp_f32_e32 v94, v94
	v_sub_f32_e32 v95, v95, v211
	v_exp_f32_e32 v95, v95
	s_waitcnt lgkmcnt(3)
	v_mfma_f32_32x32x16_bf16 v[114:129], v[234:237], v[142:145], v[114:129]
	ds_read_b128 v[234:237], v223 offset:12960
	v_sub_f32_e32 v96, v96, v211
	v_exp_f32_e32 v96, v96
	v_add_f32_e32 v241, v85, v89
	v_cvt_pk_bf16_f32 v82, v82, v83
	v_cvt_pk_bf16_f32 v83, v84, v85
	s_waitcnt lgkmcnt(3)
	v_mfma_f32_32x32x16_bf16 v[98:113], v[212:215], v[146:149], v[98:113]
	ds_read_b128 v[212:215], v223 offset:192
	v_sub_f32_e32 v97, v97, v211
	v_exp_f32_e32 v97, v97
	v_sub_f32_e32 v66, v66, v211
	v_exp_f32_e32 v66, v66
	s_waitcnt lgkmcnt(3)
	v_mfma_f32_32x32x16_bf16 v[114:129], v[218:221], v[146:149], v[114:129]
	ds_read_b128 v[218:221], v223 offset:12992
	v_sub_f32_e32 v67, v67, v211
	v_exp_f32_e32 v67, v67
	v_cvt_pk_bf16_f32 v84, v86, v87
	v_cvt_pk_bf16_f32 v85, v88, v89
	s_waitcnt lgkmcnt(3)
	v_mfma_f32_32x32x16_bf16 v[98:113], v[230:233], v[150:153], v[98:113]
	ds_read_b128 v[230:233], v223 offset:224
	v_sub_f32_e32 v68, v68, v211
	v_exp_f32_e32 v68, v68
	v_sub_f32_e32 v69, v69, v211
	v_exp_f32_e32 v69, v69
	s_waitcnt lgkmcnt(3)
	v_mfma_f32_32x32x16_bf16 v[114:129], v[234:237], v[150:153], v[114:129]
	ds_read_b128 v[234:237], v223 offset:13024
	v_sub_f32_e32 v70, v70, v211
	v_exp_f32_e32 v70, v70
	v_add_f32_e32 v238, v238, v90
	v_add_f32_e32 v239, v239, v91
	v_add_f32_e32 v240, v240, v92
	s_waitcnt lgkmcnt(3)
	v_mfma_f32_32x32x16_bf16 v[98:113], v[212:215], v[154:157], v[98:113]
	ds_read_b128 v[212:215], v223 offset:256
	v_sub_f32_e32 v71, v71, v211
	v_exp_f32_e32 v71, v71
	v_sub_f32_e32 v72, v72, v211
	v_exp_f32_e32 v72, v72
	s_waitcnt lgkmcnt(3)
	v_mfma_f32_32x32x16_bf16 v[114:129], v[218:221], v[154:157], v[114:129]
	ds_read_b128 v[218:221], v223 offset:13056
	v_sub_f32_e32 v73, v73, v211
	v_exp_f32_e32 v73, v73
	v_add_f32_e32 v241, v241, v93
	v_add_f32_e32 v238, v238, v94
	v_add_f32_e32 v239, v239, v95
	s_waitcnt lgkmcnt(3)
	v_mfma_f32_32x32x16_bf16 v[98:113], v[230:233], v[158:161], v[98:113]
	ds_read_b128 v[230:233], v223 offset:288
	v_sub_f32_e32 v74, v74, v211
	v_exp_f32_e32 v74, v74
	v_sub_f32_e32 v75, v75, v211
	v_exp_f32_e32 v75, v75
	s_waitcnt lgkmcnt(3)
	v_mfma_f32_32x32x16_bf16 v[114:129], v[234:237], v[158:161], v[114:129]
	ds_read_b128 v[234:237], v223 offset:13088
	v_sub_f32_e32 v76, v76, v211
	v_exp_f32_e32 v76, v76
	v_add_f32_e32 v240, v240, v96
	v_add_f32_e32 v241, v241, v97
	v_cvt_pk_bf16_f32 v90, v90, v91
	s_waitcnt lgkmcnt(3)
	v_mfma_f32_32x32x16_bf16 v[98:113], v[212:215], v[162:165], v[98:113]
	ds_read_b128 v[212:215], v223 offset:320
	v_sub_f32_e32 v77, v77, v211
	v_exp_f32_e32 v77, v77
	v_sub_f32_e32 v78, v78, v211
	v_exp_f32_e32 v78, v78
	s_waitcnt lgkmcnt(3)
; #define LAS __attribute__((address_space(3)))
; #define MFMA32(a, b, c) __builtin_amdgcn_mfma_f32_32x32x16_bf16((a), (b), (c), 0, 0, 0)
; DI bf16x8 pack8(const f32x16& x, int s) { u32x4 p; p.x = pk2(x[8 * s], x[8 * s + 1]); p.y = pk2(x[8 * s + 2], x[8 * s + 3]); p.z = pk2(x[8 * s + 4], x[8 * s + 5]); p.w = pk2(x[8 * s + 6], x[8 * s + 7]); return __builtin_bit_cast(bf16x8, p); }
; DI void attn_unit(LAS unsigned char* lds, const bf16_t* __restrict__ Q, const bf16_t* __restrict__ Kg, const bf16_t* __restrict__ VT, bf16_t* __restrict__ MIX, int b, int h, int c0, int nq, int desc) {
;     ...
;       for (int sx = 0; sx < 12; ++sx) { const bf16x8 a0 = *(const LAS bf16x8*)(kb2 + 32 * sx); const bf16x8 a1 = *(const LAS bf16x8*)(kb2 + 32 * KROWB + 32 * sx);
;         n0 = MFMA32(a0, qf[sx], n0); n1 = MFMA32(a1, qf[sx], n1);
; #pragma unroll
;         for (int j = 0; j < 3; ++j) { const int ei = 3 * sx + j; if (ei < 16) s0[ei] = __builtin_amdgcn_exp2f(s0[ei] - mrun); else if (ei < 32) s1[ei - 16] = __builtin_amdgcn_exp2f(s1[ei - 16] - mrun); }
;         __builtin_amdgcn_sched_barrier(0); }
;       float ps = 0.f;
; #pragma unroll
;       for (int i = 0; i < 16; ++i) ps += s0[i] + s1[i];
;       lrun += ps;
;       bf16x8 pf[4]; pf[0] = pack8(s0, 0); pf[1] = pack8(s0, 1); pf[2] = pack8(s1, 0); pf[3] = pack8(s1, 1);
;       const LAS unsigned char* vb = lds + 2 * ATT_KB + buf * ATT_VB + r31 * HROW + 16 * hh;
; #pragma unroll
;       for (int kk = 0; kk < 4; ++kk)
; #pragma unroll
;         for (int d = 0; d < 4; ++d) { const bf16x8 a = *(const LAS bf16x8*)(vb + d * 32 * HROW + 32 * kk); O[d] = MFMA32(a, pf[kk], O[d]); }
;     ...
;     s0 = n0; s1 = n1;
	v_mfma_f32_32x32x16_bf16 v[114:129], v[218:221], v[162:165], v[114:129]
	ds_read_b128 v[218:221], v223 offset:13120
	v_sub_f32_e32 v79, v79, v211
	v_exp_f32_e32 v79, v79
	v_cvt_pk_bf16_f32 v91, v92, v93
	v_cvt_pk_bf16_f32 v92, v94, v95
	v_cvt_pk_bf16_f32 v93, v96, v97
	s_waitcnt lgkmcnt(3)
	v_mfma_f32_32x32x16_bf16 v[98:113], v[230:233], v[166:169], v[98:113]
	ds_read_b128 v[230:233], v223 offset:352
	v_sub_f32_e32 v80, v80, v211
	v_exp_f32_e32 v80, v80
	v_sub_f32_e32 v81, v81, v211
	v_exp_f32_e32 v81, v81
	s_waitcnt lgkmcnt(3)
	v_mfma_f32_32x32x16_bf16 v[114:129], v[234:237], v[166:169], v[114:129]
	ds_read_b128 v[234:237], v223 offset:13152
	v_add_f32_e32 v238, v238, v66
	v_add_f32_e32 v239, v239, v67
	v_add_f32_e32 v240, v240, v68
	s_waitcnt lgkmcnt(3)
	v_mfma_f32_32x32x16_bf16 v[98:113], v[212:215], v[170:173], v[98:113]
	s_mul_i32 s34, s12, 0x4800
	v_add_u32_e32 v223, s34, v209
	ds_read_b128 v[212:215], v223 offset:51200
	v_add_f32_e32 v241, v241, v69
	v_add_f32_e32 v238, v238, v70
	v_add_f32_e32 v239, v239, v71
	s_waitcnt lgkmcnt(3)
	v_mfma_f32_32x32x16_bf16 v[114:129], v[218:221], v[170:173], v[114:129]
	ds_read_b128 v[218:221], v223 offset:55808
	v_add_f32_e32 v240, v240, v72
	v_add_f32_e32 v241, v241, v73
	v_cvt_pk_bf16_f32 v66, v66, v67
	s_waitcnt lgkmcnt(3)
	v_mfma_f32_32x32x16_bf16 v[98:113], v[230:233], v[174:177], v[98:113]
	ds_read_b128 v[230:233], v223 offset:60416
	v_cvt_pk_bf16_f32 v67, v68, v69
	v_cvt_pk_bf16_f32 v68, v70, v71
	v_cvt_pk_bf16_f32 v69, v72, v73
	s_waitcnt lgkmcnt(3)
	v_mfma_f32_32x32x16_bf16 v[114:129], v[234:237], v[174:177], v[114:129]
	ds_read_b128 v[234:237], v223 offset:65024
	v_add_f32_e32 v238, v238, v74
	v_add_f32_e32 v239, v239, v75
	v_add_f32_e32 v240, v240, v76
	s_waitcnt lgkmcnt(3)
	v_mfma_f32_32x32x16_bf16 v[50:65], v[212:215], v[82:85], v[50:65]
	ds_read_b128 v[212:215], v223 offset:51232
	v_add_f32_e32 v241, v241, v77
	v_add_f32_e32 v238, v238, v78
	v_add_f32_e32 v239, v239, v79
	s_waitcnt lgkmcnt(3)
	v_mfma_f32_32x32x16_bf16 v[34:49], v[218:221], v[82:85], v[34:49]
	ds_read_b128 v[218:221], v223 offset:55840
	v_add_f32_e32 v240, v240, v80
	v_add_f32_e32 v241, v241, v81
	v_cvt_pk_bf16_f32 v74, v74, v75
	s_waitcnt lgkmcnt(3)
	v_mfma_f32_32x32x16_bf16 v[18:33], v[230:233], v[82:85], v[18:33]
	ds_read_b128 v[230:233], v223 offset:60448
	v_cvt_pk_bf16_f32 v75, v76, v77
	v_cvt_pk_bf16_f32 v76, v78, v79
	v_cvt_pk_bf16_f32 v77, v80, v81
	s_waitcnt lgkmcnt(3)
	v_mfma_f32_32x32x16_bf16 v[2:17], v[234:237], v[82:85], v[2:17]
	ds_read_b128 v[234:237], v223 offset:65056
	v_add_f32_e32 v238, v238, v239
	v_add_f32_e32 v240, v240, v241
	s_waitcnt lgkmcnt(3)
	v_mfma_f32_32x32x16_bf16 v[50:65], v[212:215], v[90:93], v[50:65]
	ds_read_b128 v[212:215], v223 offset:51264
	v_add_f32_e32 v0, v238, v240
	s_waitcnt lgkmcnt(3)
	v_mfma_f32_32x32x16_bf16 v[34:49], v[218:221], v[90:93], v[34:49]
	ds_read_b128 v[218:221], v223 offset:55872
	v_add_f32_e32 v210, v210, v0
	s_waitcnt lgkmcnt(3)
	v_mfma_f32_32x32x16_bf16 v[18:33], v[230:233], v[90:93], v[18:33]
	ds_read_b128 v[230:233], v223 offset:60480
	s_waitcnt lgkmcnt(3)
	v_mfma_f32_32x32x16_bf16 v[2:17], v[234:237], v[90:93], v[2:17]
	ds_read_b128 v[234:237], v223 offset:65088
	s_waitcnt lgkmcnt(3)
	v_mfma_f32_32x32x16_bf16 v[50:65], v[212:215], v[66:69], v[50:65]
	ds_read_b128 v[212:215], v223 offset:51296
	s_waitcnt lgkmcnt(3)
	v_mfma_f32_32x32x16_bf16 v[34:49], v[218:221], v[66:69], v[34:49]
	ds_read_b128 v[218:221], v223 offset:55904
	s_waitcnt lgkmcnt(3)
	v_mfma_f32_32x32x16_bf16 v[18:33], v[230:233], v[66:69], v[18:33]
	ds_read_b128 v[230:233], v223 offset:60512
	s_waitcnt lgkmcnt(3)
	v_mfma_f32_32x32x16_bf16 v[2:17], v[234:237], v[66:69], v[2:17]
	ds_read_b128 v[234:237], v223 offset:65120
	s_waitcnt lgkmcnt(3)
	v_mfma_f32_32x32x16_bf16 v[50:65], v[212:215], v[74:77], v[50:65]
	s_waitcnt lgkmcnt(2)
	v_mfma_f32_32x32x16_bf16 v[34:49], v[218:221], v[74:77], v[34:49]
	s_waitcnt lgkmcnt(1)
	v_mfma_f32_32x32x16_bf16 v[18:33], v[230:233], v[74:77], v[18:33]
	s_waitcnt lgkmcnt(0)
	v_mfma_f32_32x32x16_bf16 v[2:17], v[234:237], v[74:77], v[2:17]
	v_mov_b64_e32 v[82:83], v[98:99]
	v_mov_b64_e32 v[66:67], v[114:115]
	v_mov_b64_e32 v[84:85], v[100:101]
	v_mov_b64_e32 v[86:87], v[102:103]
	v_mov_b64_e32 v[88:89], v[104:105]
	v_mov_b64_e32 v[90:91], v[106:107]
	v_mov_b64_e32 v[92:93], v[108:109]
	v_mov_b64_e32 v[94:95], v[110:111]
	v_mov_b64_e32 v[96:97], v[112:113]
	v_mov_b64_e32 v[68:69], v[116:117]
	v_mov_b64_e32 v[70:71], v[118:119]
	v_mov_b64_e32 v[72:73], v[120:121]
	v_mov_b64_e32 v[74:75], v[122:123]
	v_mov_b64_e32 v[76:77], v[124:125]
	v_mov_b64_e32 v[78:79], v[126:127]
	v_mov_b64_e32 v[80:81], v[128:129]
	s_or_b64 exec, exec, s[30:31]
	s_andn2_b64 vcc, exec, s[26:27]
	s_cbranch_vccz .LBB0_560

; #define LAS __attribute__((address_space(3)))
; #define MFMA32(a, b, c) __builtin_amdgcn_mfma_f32_32x32x16_bf16((a), (b), (c), 0, 0, 0)
; DI int perm32k(int i) { return (i & 0x13) | ((i & 8) >> 1) | ((i & 4) << 1); }
; DI bf16x8 pack8(const f32x16& x, int s) { u32x4 p; p.x = pk2(x[8 * s], x[8 * s + 1]); p.y = pk2(x[8 * s + 2], x[8 * s + 3]); p.z = pk2(x[8 * s + 4], x[8 * s + 5]); p.w = pk2(x[8 * s + 6], x[8 * s + 7]); return __builtin_bit_cast(bf16x8, p); }
; DI void attn_unit(LAS unsigned char* lds, const bf16_t* __restrict__ Q, const bf16_t* __restrict__ Kg, const bf16_t* __restrict__ VT, bf16_t* __restrict__ MIX, int b, int h, int c0, int nq, int desc) {
;     ...
;       for (int i = 0; i < 16; ++i) { n0[i] = 0.f; n1[i] = 0.f; }
;       const LAS unsigned char* kb2 = lds + (buf ^ 1) * ATT_KB + perm32k(r31) * KROWB + 16 * hh;
;       __builtin_amdgcn_sched_barrier(0);
; #pragma unroll
;       for (int sx = 0; sx < 12; ++sx) { const bf16x8 a0 = *(const LAS bf16x8*)(kb2 + 32 * sx); const bf16x8 a1 = *(const LAS bf16x8*)(kb2 + 32 * KROWB + 32 * sx);
;         n0 = MFMA32(a0, qf[sx], n0); n1 = MFMA32(a1, qf[sx], n1);
; #pragma unroll
;         for (int j = 0; j < 3; ++j) { const int ei = 3 * sx + j; if (ei < 16) s0[ei] = __builtin_amdgcn_exp2f(s0[ei] - mrun); else if (ei < 32) s1[ei - 16] = __builtin_amdgcn_exp2f(s1[ei - 16] - mrun); }
;         __builtin_amdgcn_sched_barrier(0); }
;       float ps = 0.f;
; #pragma unroll
;       for (int i = 0; i < 16; ++i) ps += s0[i] + s1[i];
;       lrun += ps;
;       bf16x8 pf[4]; pf[0] = pack8(s0, 0); pf[1] = pack8(s0, 1); pf[2] = pack8(s1, 0); pf[3] = pack8(s1, 1);
.LBB0_583:
	s_xor_b32 s30, s71, 1
	s_mulk_i32 s30, 0x6400
	v_add_u32_e32 v95, s30, v81
	ds_read_b128 v[2:5], v95
	ds_read_b128 v[6:9], v95 offset:12800
	ds_read_b128 v[10:13], v95 offset:32
	ds_read_b128 v[236:239], v95 offset:12832
	v_sub_f32_e32 v112, v112, v234
	v_exp_f32_e32 v112, v112
	v_sub_f32_e32 v113, v113, v234
	v_exp_f32_e32 v113, v113
	v_sub_f32_e32 v114, v114, v234
	v_exp_f32_e32 v114, v114
	s_waitcnt lgkmcnt(3)
	v_mfma_f32_32x32x16_bf16 v[128:143], v[2:5], v[82:85], 0
	ds_read_b128 v[2:5], v95 offset:64
	v_sub_f32_e32 v115, v115, v234
	v_exp_f32_e32 v115, v115
	v_sub_f32_e32 v116, v116, v234
	v_exp_f32_e32 v116, v116
	s_waitcnt lgkmcnt(3)
	v_mfma_f32_32x32x16_bf16 v[144:159], v[6:9], v[82:85], 0
	ds_read_b128 v[6:9], v95 offset:12864
	v_sub_f32_e32 v117, v117, v234
	v_exp_f32_e32 v117, v117
	s_waitcnt lgkmcnt(3)
	v_mfma_f32_32x32x16_bf16 v[128:143], v[10:13], v[86:89], v[128:143]
	ds_read_b128 v[10:13], v95 offset:96
	v_sub_f32_e32 v118, v118, v234
	v_exp_f32_e32 v118, v118
	v_sub_f32_e32 v119, v119, v234
	v_exp_f32_e32 v119, v119
	s_waitcnt lgkmcnt(3)
	v_mfma_f32_32x32x16_bf16 v[144:159], v[236:239], v[86:89], v[144:159]
	ds_read_b128 v[236:239], v95 offset:12896
	v_sub_f32_e32 v120, v120, v234
	v_exp_f32_e32 v120, v120
	s_waitcnt lgkmcnt(3)
	v_mfma_f32_32x32x16_bf16 v[128:143], v[2:5], v[90:93], v[128:143]
	ds_read_b128 v[2:5], v95 offset:128
	v_sub_f32_e32 v121, v121, v234
	v_exp_f32_e32 v121, v121
	v_sub_f32_e32 v122, v122, v234
	v_exp_f32_e32 v122, v122
	s_waitcnt lgkmcnt(3)
	v_mfma_f32_32x32x16_bf16 v[144:159], v[6:9], v[90:93], v[144:159]
	ds_read_b128 v[6:9], v95 offset:12928
	v_sub_f32_e32 v123, v123, v234
	v_exp_f32_e32 v123, v123
	v_add_f32_e32 v14, v112, v116
	v_add_f32_e32 v15, v113, v117
	v_add_f32_e32 v240, v114, v118
	s_waitcnt lgkmcnt(3)
	v_mfma_f32_32x32x16_bf16 v[128:143], v[10:13], v[180:183], v[128:143]
	ds_read_b128 v[10:13], v95 offset:160
	v_sub_f32_e32 v124, v124, v234
	v_exp_f32_e32 v124, v124
	v_sub_f32_e32 v125, v125, v234
	v_exp_f32_e32 v125, v125
	s_waitcnt lgkmcnt(3)
	v_mfma_f32_32x32x16_bf16 v[144:159], v[236:239], v[180:183], v[144:159]
	ds_read_b128 v[236:239], v95 offset:12960
	v_sub_f32_e32 v126, v126, v234
	v_exp_f32_e32 v126, v126
	v_add_f32_e32 v241, v115, v119
	v_cvt_pk_bf16_f32 v112, v112, v113
	v_cvt_pk_bf16_f32 v113, v114, v115
	s_waitcnt lgkmcnt(3)
	v_mfma_f32_32x32x16_bf16 v[128:143], v[2:5], v[184:187], v[128:143]
	ds_read_b128 v[2:5], v95 offset:192
	v_sub_f32_e32 v127, v127, v234
	v_exp_f32_e32 v127, v127
	v_sub_f32_e32 v96, v96, v234
	v_exp_f32_e32 v96, v96
	s_waitcnt lgkmcnt(3)
	v_mfma_f32_32x32x16_bf16 v[144:159], v[6:9], v[184:187], v[144:159]
	ds_read_b128 v[6:9], v95 offset:12992
	v_sub_f32_e32 v97, v97, v234
	v_exp_f32_e32 v97, v97
	v_cvt_pk_bf16_f32 v114, v116, v117
	v_cvt_pk_bf16_f32 v115, v118, v119
	s_waitcnt lgkmcnt(3)
	v_mfma_f32_32x32x16_bf16 v[128:143], v[10:13], v[188:191], v[128:143]
	ds_read_b128 v[10:13], v95 offset:224
	v_sub_f32_e32 v98, v98, v234
	v_exp_f32_e32 v98, v98
	v_sub_f32_e32 v99, v99, v234
	v_exp_f32_e32 v99, v99
	s_waitcnt lgkmcnt(3)
	v_mfma_f32_32x32x16_bf16 v[144:159], v[236:239], v[188:191], v[144:159]
	ds_read_b128 v[236:239], v95 offset:13024
	v_sub_f32_e32 v100, v100, v234
	v_exp_f32_e32 v100, v100
	v_add_f32_e32 v14, v14, v120
	v_add_f32_e32 v15, v15, v121
	v_add_f32_e32 v240, v240, v122
	s_waitcnt lgkmcnt(3)
	v_mfma_f32_32x32x16_bf16 v[128:143], v[2:5], v[192:195], v[128:143]
	ds_read_b128 v[2:5], v95 offset:256
	v_sub_f32_e32 v101, v101, v234
	v_exp_f32_e32 v101, v101
	v_sub_f32_e32 v102, v102, v234
	v_exp_f32_e32 v102, v102
	s_waitcnt lgkmcnt(3)
	v_mfma_f32_32x32x16_bf16 v[144:159], v[6:9], v[192:195], v[144:159]
	ds_read_b128 v[6:9], v95 offset:13056
	v_sub_f32_e32 v103, v103, v234
	v_exp_f32_e32 v103, v103
	v_add_f32_e32 v241, v241, v123
	v_add_f32_e32 v14, v14, v124
	v_add_f32_e32 v15, v15, v125
	s_waitcnt lgkmcnt(3)
	v_mfma_f32_32x32x16_bf16 v[128:143], v[10:13], v[196:199], v[128:143]
	ds_read_b128 v[10:13], v95 offset:288
	v_sub_f32_e32 v104, v104, v234
	v_exp_f32_e32 v104, v104
	v_sub_f32_e32 v105, v105, v234
	v_exp_f32_e32 v105, v105
	s_waitcnt lgkmcnt(3)
	v_mfma_f32_32x32x16_bf16 v[144:159], v[236:239], v[196:199], v[144:159]
	ds_read_b128 v[236:239], v95 offset:13088
	v_sub_f32_e32 v106, v106, v234
	v_exp_f32_e32 v106, v106
	v_add_f32_e32 v240, v240, v126
	v_add_f32_e32 v241, v241, v127
	v_cvt_pk_bf16_f32 v120, v120, v121
	s_waitcnt lgkmcnt(3)
; #define LAS __attribute__((address_space(3)))
; #define MFMA32(a, b, c) __builtin_amdgcn_mfma_f32_32x32x16_bf16((a), (b), (c), 0, 0, 0)
; DI bf16x8 pack8(const f32x16& x, int s) { u32x4 p; p.x = pk2(x[8 * s], x[8 * s + 1]); p.y = pk2(x[8 * s + 2], x[8 * s + 3]); p.z = pk2(x[8 * s + 4], x[8 * s + 5]); p.w = pk2(x[8 * s + 6], x[8 * s + 7]); return __builtin_bit_cast(bf16x8, p); }
; DI void attn_unit(LAS unsigned char* lds, const bf16_t* __restrict__ Q, const bf16_t* __restrict__ Kg, const bf16_t* __restrict__ VT, bf16_t* __restrict__ MIX, int b, int h, int c0, int nq, int desc) {
;     ...
;       for (int sx = 0; sx < 12; ++sx) { const bf16x8 a0 = *(const LAS bf16x8*)(kb2 + 32 * sx); const bf16x8 a1 = *(const LAS bf16x8*)(kb2 + 32 * KROWB + 32 * sx);
;         n0 = MFMA32(a0, qf[sx], n0); n1 = MFMA32(a1, qf[sx], n1);
; #pragma unroll
;         for (int j = 0; j < 3; ++j) { const int ei = 3 * sx + j; if (ei < 16) s0[ei] = __builtin_amdgcn_exp2f(s0[ei] - mrun); else if (ei < 32) s1[ei - 16] = __builtin_amdgcn_exp2f(s1[ei - 16] - mrun); }
;         __builtin_amdgcn_sched_barrier(0); }
;       float ps = 0.f;
; #pragma unroll
;       for (int i = 0; i < 16; ++i) ps += s0[i] + s1[i];
;       lrun += ps;
;       bf16x8 pf[4]; pf[0] = pack8(s0, 0); pf[1] = pack8(s0, 1); pf[2] = pack8(s1, 0); pf[3] = pack8(s1, 1);
;       const LAS unsigned char* vb = lds + 2 * ATT_KB + buf * ATT_VB + r31 * HROW + 16 * hh;
; #pragma unroll
;       for (int kk = 0; kk < 4; ++kk)
; #pragma unroll
;         for (int d = 0; d < 4; ++d) { const bf16x8 a = *(const LAS bf16x8*)(vb + d * 32 * HROW + 32 * kk); O[d] = MFMA32(a, pf[kk], O[d]); }
	v_mfma_f32_32x32x16_bf16 v[128:143], v[2:5], v[200:203], v[128:143]
	ds_read_b128 v[2:5], v95 offset:320
	v_sub_f32_e32 v107, v107, v234
	v_exp_f32_e32 v107, v107
	v_sub_f32_e32 v108, v108, v234
	v_exp_f32_e32 v108, v108
	s_waitcnt lgkmcnt(3)
	v_mfma_f32_32x32x16_bf16 v[144:159], v[6:9], v[200:203], v[144:159]
	ds_read_b128 v[6:9], v95 offset:13120
	v_sub_f32_e32 v109, v109, v234
	v_exp_f32_e32 v109, v109
	v_cvt_pk_bf16_f32 v121, v122, v123
	v_cvt_pk_bf16_f32 v122, v124, v125
	v_cvt_pk_bf16_f32 v123, v126, v127
	s_waitcnt lgkmcnt(3)
	v_mfma_f32_32x32x16_bf16 v[128:143], v[10:13], v[204:207], v[128:143]
	ds_read_b128 v[10:13], v95 offset:352
	v_sub_f32_e32 v110, v110, v234
	v_exp_f32_e32 v110, v110
	v_sub_f32_e32 v111, v111, v234
	v_exp_f32_e32 v111, v111
	s_waitcnt lgkmcnt(3)
	v_mfma_f32_32x32x16_bf16 v[144:159], v[236:239], v[204:207], v[144:159]
	ds_read_b128 v[236:239], v95 offset:13152
	v_add_f32_e32 v14, v14, v96
	v_add_f32_e32 v15, v15, v97
	v_add_f32_e32 v240, v240, v98
	s_waitcnt lgkmcnt(3)
	v_mfma_f32_32x32x16_bf16 v[128:143], v[2:5], v[208:211], v[128:143]
	s_mul_i32 s30, s71, 0x4800
	v_add_u32_e32 v95, s30, v232
	ds_read_b128 v[2:5], v95 offset:51200
	v_add_f32_e32 v241, v241, v99
	v_add_f32_e32 v14, v14, v100
	v_add_f32_e32 v15, v15, v101
	s_waitcnt lgkmcnt(3)
	v_mfma_f32_32x32x16_bf16 v[144:159], v[6:9], v[208:211], v[144:159]
	ds_read_b128 v[6:9], v95 offset:55808
	v_add_f32_e32 v240, v240, v102
	v_add_f32_e32 v241, v241, v103
	v_cvt_pk_bf16_f32 v96, v96, v97
	s_waitcnt lgkmcnt(3)
	v_mfma_f32_32x32x16_bf16 v[128:143], v[10:13], v[212:215], v[128:143]
	ds_read_b128 v[10:13], v95 offset:60416
	v_cvt_pk_bf16_f32 v97, v98, v99
	v_cvt_pk_bf16_f32 v98, v100, v101
	v_cvt_pk_bf16_f32 v99, v102, v103
	s_waitcnt lgkmcnt(3)
	v_mfma_f32_32x32x16_bf16 v[144:159], v[236:239], v[212:215], v[144:159]
	ds_read_b128 v[236:239], v95 offset:65024
	v_add_f32_e32 v14, v14, v104
	v_add_f32_e32 v15, v15, v105
	v_add_f32_e32 v240, v240, v106
	s_waitcnt lgkmcnt(3)
	v_mfma_f32_32x32x16_bf16 v[64:79], v[2:5], v[112:115], v[64:79]
	ds_read_b128 v[2:5], v95 offset:51232
	v_add_f32_e32 v241, v241, v107
	v_add_f32_e32 v14, v14, v108
	v_add_f32_e32 v15, v15, v109
	s_waitcnt lgkmcnt(3)
	v_mfma_f32_32x32x16_bf16 v[48:63], v[6:9], v[112:115], v[48:63]
	ds_read_b128 v[6:9], v95 offset:55840
	v_add_f32_e32 v240, v240, v110
	v_add_f32_e32 v241, v241, v111
	v_cvt_pk_bf16_f32 v104, v104, v105
	s_waitcnt lgkmcnt(3)
	v_mfma_f32_32x32x16_bf16 v[32:47], v[10:13], v[112:115], v[32:47]
	ds_read_b128 v[10:13], v95 offset:60448
	v_cvt_pk_bf16_f32 v105, v106, v107
	v_cvt_pk_bf16_f32 v106, v108, v109
	v_cvt_pk_bf16_f32 v107, v110, v111
	s_waitcnt lgkmcnt(3)
	v_mfma_f32_32x32x16_bf16 v[16:31], v[236:239], v[112:115], v[16:31]
	ds_read_b128 v[236:239], v95 offset:65056
	v_add_f32_e32 v14, v14, v15
	v_add_f32_e32 v240, v240, v241
	s_waitcnt lgkmcnt(3)
	v_mfma_f32_32x32x16_bf16 v[64:79], v[2:5], v[120:123], v[64:79]
	ds_read_b128 v[2:5], v95 offset:51264
	v_add_f32_e32 v0, v14, v240
	s_waitcnt lgkmcnt(3)
	v_mfma_f32_32x32x16_bf16 v[48:63], v[6:9], v[120:123], v[48:63]
	ds_read_b128 v[6:9], v95 offset:55872
	v_add_f32_e32 v80, v80, v0
	s_waitcnt lgkmcnt(3)
	v_mfma_f32_32x32x16_bf16 v[32:47], v[10:13], v[120:123], v[32:47]
	ds_read_b128 v[10:13], v95 offset:60480
	s_waitcnt lgkmcnt(3)
	v_mfma_f32_32x32x16_bf16 v[16:31], v[236:239], v[120:123], v[16:31]
	ds_read_b128 v[236:239], v95 offset:65088
	s_waitcnt lgkmcnt(3)
	v_mfma_f32_32x32x16_bf16 v[64:79], v[2:5], v[96:99], v[64:79]
	ds_read_b128 v[2:5], v95 offset:51296
	s_waitcnt lgkmcnt(3)
	v_mfma_f32_32x32x16_bf16 v[48:63], v[6:9], v[96:99], v[48:63]
	ds_read_b128 v[6:9], v95 offset:55904
	s_waitcnt lgkmcnt(3)
	v_mfma_f32_32x32x16_bf16 v[32:47], v[10:13], v[96:99], v[32:47]
	ds_read_b128 v[10:13], v95 offset:60512
	s_waitcnt lgkmcnt(3)
	v_mfma_f32_32x32x16_bf16 v[16:31], v[236:239], v[96:99], v[16:31]
	ds_read_b128 v[236:239], v95 offset:65120
	s_waitcnt lgkmcnt(3)
	v_mfma_f32_32x32x16_bf16 v[64:79], v[2:5], v[104:107], v[64:79]
	s_waitcnt lgkmcnt(2)
	v_mfma_f32_32x32x16_bf16 v[48:63], v[6:9], v[104:107], v[48:63]
	s_waitcnt lgkmcnt(1)
	v_mfma_f32_32x32x16_bf16 v[32:47], v[10:13], v[104:107], v[32:47]
	s_waitcnt lgkmcnt(0)
	v_mfma_f32_32x32x16_bf16 v[16:31], v[236:239], v[104:107], v[16:31]
	s_or_b64 exec, exec, s[6:7]
	s_andn2_b64 vcc, exec, s[26:27]
	s_cbranch_vccz .LBB0_592

; #define LAS __attribute__((address_space(3)))
; #define MFMA32(a, b, c) __builtin_amdgcn_mfma_f32_32x32x16_bf16((a), (b), (c), 0, 0, 0)
; DI int perm32k(int i) { return (i & 0x13) | ((i & 8) >> 1) | ((i & 4) << 1); }
; DI bf16x8 pack8(const f32x16& x, int s) { u32x4 p; p.x = pk2(x[8 * s], x[8 * s + 1]); p.y = pk2(x[8 * s + 2], x[8 * s + 3]); p.z = pk2(x[8 * s + 4], x[8 * s + 5]); p.w = pk2(x[8 * s + 6], x[8 * s + 7]); return __builtin_bit_cast(bf16x8, p); }
; DI void attn_unit(LAS unsigned char* lds, const bf16_t* __restrict__ Q, const bf16_t* __restrict__ Kg, const bf16_t* __restrict__ VT, bf16_t* __restrict__ MIX, int b, int h, int c0, int nq, int desc) {
;     ...
;       for (int i = 0; i < 16; ++i) { n0[i] = 0.f; n1[i] = 0.f; }
;       const LAS unsigned char* kb2 = lds + (buf ^ 1) * ATT_KB + perm32k(r31) * KROWB + 16 * hh;
;       __builtin_amdgcn_sched_barrier(0);
; #pragma unroll
;       for (int sx = 0; sx < 12; ++sx) { const bf16x8 a0 = *(const LAS bf16x8*)(kb2 + 32 * sx); const bf16x8 a1 = *(const LAS bf16x8*)(kb2 + 32 * KROWB + 32 * sx);
;         n0 = MFMA32(a0, qf[sx], n0); n1 = MFMA32(a1, qf[sx], n1);
; #pragma unroll
;         for (int j = 0; j < 3; ++j) { const int ei = 3 * sx + j; if (ei < 16) s0[ei] = __builtin_amdgcn_exp2f(s0[ei] - mrun); else if (ei < 32) s1[ei - 16] = __builtin_amdgcn_exp2f(s1[ei - 16] - mrun); }
;         __builtin_amdgcn_sched_barrier(0); }
;       float ps = 0.f;
; #pragma unroll
;       for (int i = 0; i < 16; ++i) ps += s0[i] + s1[i];
;       lrun += ps;
;       bf16x8 pf[4]; pf[0] = pack8(s0, 0); pf[1] = pack8(s0, 1); pf[2] = pack8(s1, 0); pf[3] = pack8(s1, 1);
.LBB0_2562:
	s_xor_b32 s0, s12, 1
	s_mulk_i32 s0, 0x6400
	v_add_u32_e32 v223, s0, v208
	ds_read_b128 v[212:215], v223
	ds_read_b128 v[218:221], v223 offset:12800
	ds_read_b128 v[230:233], v223 offset:32
	ds_read_b128 v[234:237], v223 offset:12832
	v_sub_f32_e32 v82, v82, v211
	v_exp_f32_e32 v82, v82
	v_sub_f32_e32 v83, v83, v211
	v_exp_f32_e32 v83, v83
	v_sub_f32_e32 v84, v84, v211
	v_exp_f32_e32 v84, v84
	s_waitcnt lgkmcnt(3)
	v_mfma_f32_32x32x16_bf16 v[98:113], v[212:215], v[130:133], 0
	ds_read_b128 v[212:215], v223 offset:64
	v_sub_f32_e32 v85, v85, v211
	v_exp_f32_e32 v85, v85
	v_sub_f32_e32 v86, v86, v211
	v_exp_f32_e32 v86, v86
	s_waitcnt lgkmcnt(3)
	v_mfma_f32_32x32x16_bf16 v[114:129], v[218:221], v[130:133], 0
	ds_read_b128 v[218:221], v223 offset:12864
	v_sub_f32_e32 v87, v87, v211
	v_exp_f32_e32 v87, v87
	s_waitcnt lgkmcnt(3)
	v_mfma_f32_32x32x16_bf16 v[98:113], v[230:233], v[134:137], v[98:113]
	ds_read_b128 v[230:233], v223 offset:96
	v_sub_f32_e32 v88, v88, v211
	v_exp_f32_e32 v88, v88
	v_sub_f32_e32 v89, v89, v211
	v_exp_f32_e32 v89, v89
	s_waitcnt lgkmcnt(3)
	v_mfma_f32_32x32x16_bf16 v[114:129], v[234:237], v[134:137], v[114:129]
	ds_read_b128 v[234:237], v223 offset:12896
	v_sub_f32_e32 v90, v90, v211
	v_exp_f32_e32 v90, v90
	s_waitcnt lgkmcnt(3)
	v_mfma_f32_32x32x16_bf16 v[98:113], v[212:215], v[138:141], v[98:113]
	ds_read_b128 v[212:215], v223 offset:128
	v_sub_f32_e32 v91, v91, v211
	v_exp_f32_e32 v91, v91
	v_sub_f32_e32 v92, v92, v211
	v_exp_f32_e32 v92, v92
	s_waitcnt lgkmcnt(3)
	v_mfma_f32_32x32x16_bf16 v[114:129], v[218:221], v[138:141], v[114:129]
	ds_read_b128 v[218:221], v223 offset:12928
	v_sub_f32_e32 v93, v93, v211
	v_exp_f32_e32 v93, v93
	v_add_f32_e32 v238, v82, v86
	v_add_f32_e32 v239, v83, v87
	v_add_f32_e32 v240, v84, v88
	s_waitcnt lgkmcnt(3)
	v_mfma_f32_32x32x16_bf16 v[98:113], v[230:233], v[142:145], v[98:113]
	ds_read_b128 v[230:233], v223 offset:160
	v_sub_f32_e32 v94, v94, v211
	v_exp_f32_e32 v94, v94
	v_sub_f32_e32 v95, v95, v211
	v_exp_f32_e32 v95, v95
	s_waitcnt lgkmcnt(3)
	v_mfma_f32_32x32x16_bf16 v[114:129], v[234:237], v[142:145], v[114:129]
	ds_read_b128 v[234:237], v223 offset:12960
	v_sub_f32_e32 v96, v96, v211
	v_exp_f32_e32 v96, v96
	v_add_f32_e32 v241, v85, v89
	v_cvt_pk_bf16_f32 v82, v82, v83
	v_cvt_pk_bf16_f32 v83, v84, v85
	s_waitcnt lgkmcnt(3)
	v_mfma_f32_32x32x16_bf16 v[98:113], v[212:215], v[146:149], v[98:113]
	ds_read_b128 v[212:215], v223 offset:192
	v_sub_f32_e32 v97, v97, v211
	v_exp_f32_e32 v97, v97
	v_sub_f32_e32 v66, v66, v211
	v_exp_f32_e32 v66, v66
	s_waitcnt lgkmcnt(3)
	v_mfma_f32_32x32x16_bf16 v[114:129], v[218:221], v[146:149], v[114:129]
	ds_read_b128 v[218:221], v223 offset:12992
	v_sub_f32_e32 v67, v67, v211
	v_exp_f32_e32 v67, v67
	v_cvt_pk_bf16_f32 v84, v86, v87
	v_cvt_pk_bf16_f32 v85, v88, v89
	s_waitcnt lgkmcnt(3)
	v_mfma_f32_32x32x16_bf16 v[98:113], v[230:233], v[150:153], v[98:113]
	ds_read_b128 v[230:233], v223 offset:224
	v_sub_f32_e32 v68, v68, v211
	v_exp_f32_e32 v68, v68
	v_sub_f32_e32 v69, v69, v211
	v_exp_f32_e32 v69, v69
	s_waitcnt lgkmcnt(3)
	v_mfma_f32_32x32x16_bf16 v[114:129], v[234:237], v[150:153], v[114:129]
	ds_read_b128 v[234:237], v223 offset:13024
	v_sub_f32_e32 v70, v70, v211
	v_exp_f32_e32 v70, v70
	v_add_f32_e32 v238, v238, v90
	v_add_f32_e32 v239, v239, v91
	v_add_f32_e32 v240, v240, v92
	s_waitcnt lgkmcnt(3)
	v_mfma_f32_32x32x16_bf16 v[98:113], v[212:215], v[154:157], v[98:113]
	ds_read_b128 v[212:215], v223 offset:256
	v_sub_f32_e32 v71, v71, v211
	v_exp_f32_e32 v71, v71
	v_sub_f32_e32 v72, v72, v211
	v_exp_f32_e32 v72, v72
	s_waitcnt lgkmcnt(3)
	v_mfma_f32_32x32x16_bf16 v[114:129], v[218:221], v[154:157], v[114:129]
	ds_read_b128 v[218:221], v223 offset:13056
	v_sub_f32_e32 v73, v73, v211
	v_exp_f32_e32 v73, v73
	v_add_f32_e32 v241, v241, v93
	v_add_f32_e32 v238, v238, v94
	v_add_f32_e32 v239, v239, v95
	s_waitcnt lgkmcnt(3)
	v_mfma_f32_32x32x16_bf16 v[98:113], v[230:233], v[158:161], v[98:113]
	ds_read_b128 v[230:233], v223 offset:288
	v_sub_f32_e32 v74, v74, v211
	v_exp_f32_e32 v74, v74
	v_sub_f32_e32 v75, v75, v211
	v_exp_f32_e32 v75, v75
	s_waitcnt lgkmcnt(3)
	v_mfma_f32_32x32x16_bf16 v[114:129], v[234:237], v[158:161], v[114:129]
	ds_read_b128 v[234:237], v223 offset:13088
	v_sub_f32_e32 v76, v76, v211
	v_exp_f32_e32 v76, v76
	v_add_f32_e32 v240, v240, v96
	v_add_f32_e32 v241, v241, v97
	v_cvt_pk_bf16_f32 v90, v90, v91
	s_waitcnt lgkmcnt(3)
	v_mfma_f32_32x32x16_bf16 v[98:113], v[212:215], v[162:165], v[98:113]
	ds_read_b128 v[212:215], v223 offset:320
	v_sub_f32_e32 v77, v77, v211
	v_exp_f32_e32 v77, v77
	v_sub_f32_e32 v78, v78, v211
	v_exp_f32_e32 v78, v78
	s_waitcnt lgkmcnt(3)
; #define LAS __attribute__((address_space(3)))
; #define MFMA32(a, b, c) __builtin_amdgcn_mfma_f32_32x32x16_bf16((a), (b), (c), 0, 0, 0)
; DI bf16x8 pack8(const f32x16& x, int s) { u32x4 p; p.x = pk2(x[8 * s], x[8 * s + 1]); p.y = pk2(x[8 * s + 2], x[8 * s + 3]); p.z = pk2(x[8 * s + 4], x[8 * s + 5]); p.w = pk2(x[8 * s + 6], x[8 * s + 7]); return __builtin_bit_cast(bf16x8, p); }
; DI void attn_unit(LAS unsigned char* lds, const bf16_t* __restrict__ Q, const bf16_t* __restrict__ Kg, const bf16_t* __restrict__ VT, bf16_t* __restrict__ MIX, int b, int h, int c0, int nq, int desc) {
;     ...
;       for (int sx = 0; sx < 12; ++sx) { const bf16x8 a0 = *(const LAS bf16x8*)(kb2 + 32 * sx); const bf16x8 a1 = *(const LAS bf16x8*)(kb2 + 32 * KROWB + 32 * sx);
;         n0 = MFMA32(a0, qf[sx], n0); n1 = MFMA32(a1, qf[sx], n1);
; #pragma unroll
;         for (int j = 0; j < 3; ++j) { const int ei = 3 * sx + j; if (ei < 16) s0[ei] = __builtin_amdgcn_exp2f(s0[ei] - mrun); else if (ei < 32) s1[ei - 16] = __builtin_amdgcn_exp2f(s1[ei - 16] - mrun); }
;         __builtin_amdgcn_sched_barrier(0); }
;       float ps = 0.f;
; #pragma unroll
;       for (int i = 0; i < 16; ++i) ps += s0[i] + s1[i];
;       lrun += ps;
;       bf16x8 pf[4]; pf[0] = pack8(s0, 0); pf[1] = pack8(s0, 1); pf[2] = pack8(s1, 0); pf[3] = pack8(s1, 1);
;       const LAS unsigned char* vb = lds + 2 * ATT_KB + buf * ATT_VB + r31 * HROW + 16 * hh;
; #pragma unroll
;       for (int kk = 0; kk < 4; ++kk)
; #pragma unroll
;         for (int d = 0; d < 4; ++d) { const bf16x8 a = *(const LAS bf16x8*)(vb + d * 32 * HROW + 32 * kk); O[d] = MFMA32(a, pf[kk], O[d]); }
;     ...
;     s0 = n0; s1 = n1;
	v_mfma_f32_32x32x16_bf16 v[114:129], v[218:221], v[162:165], v[114:129]
	ds_read_b128 v[218:221], v223 offset:13120
	v_sub_f32_e32 v79, v79, v211
	v_exp_f32_e32 v79, v79
	v_cvt_pk_bf16_f32 v91, v92, v93
	v_cvt_pk_bf16_f32 v92, v94, v95
	v_cvt_pk_bf16_f32 v93, v96, v97
	s_waitcnt lgkmcnt(3)
	v_mfma_f32_32x32x16_bf16 v[98:113], v[230:233], v[166:169], v[98:113]
	ds_read_b128 v[230:233], v223 offset:352
	v_sub_f32_e32 v80, v80, v211
	v_exp_f32_e32 v80, v80
	v_sub_f32_e32 v81, v81, v211
	v_exp_f32_e32 v81, v81
	s_waitcnt lgkmcnt(3)
	v_mfma_f32_32x32x16_bf16 v[114:129], v[234:237], v[166:169], v[114:129]
	ds_read_b128 v[234:237], v223 offset:13152
	v_add_f32_e32 v238, v238, v66
	v_add_f32_e32 v239, v239, v67
	v_add_f32_e32 v240, v240, v68
	s_waitcnt lgkmcnt(3)
	v_mfma_f32_32x32x16_bf16 v[98:113], v[212:215], v[170:173], v[98:113]
	s_mul_i32 s0, s12, 0x4800
	v_add_u32_e32 v223, s0, v209
	ds_read_b128 v[212:215], v223 offset:51200
	v_add_f32_e32 v241, v241, v69
	v_add_f32_e32 v238, v238, v70
	v_add_f32_e32 v239, v239, v71
	s_waitcnt lgkmcnt(3)
	v_mfma_f32_32x32x16_bf16 v[114:129], v[218:221], v[170:173], v[114:129]
	ds_read_b128 v[218:221], v223 offset:55808
	v_add_f32_e32 v240, v240, v72
	v_add_f32_e32 v241, v241, v73
	v_cvt_pk_bf16_f32 v66, v66, v67
	s_waitcnt lgkmcnt(3)
	v_mfma_f32_32x32x16_bf16 v[98:113], v[230:233], v[174:177], v[98:113]
	ds_read_b128 v[230:233], v223 offset:60416
	v_cvt_pk_bf16_f32 v67, v68, v69
	v_cvt_pk_bf16_f32 v68, v70, v71
	v_cvt_pk_bf16_f32 v69, v72, v73
	s_waitcnt lgkmcnt(3)
	v_mfma_f32_32x32x16_bf16 v[114:129], v[234:237], v[174:177], v[114:129]
	ds_read_b128 v[234:237], v223 offset:65024
	v_add_f32_e32 v238, v238, v74
	v_add_f32_e32 v239, v239, v75
	v_add_f32_e32 v240, v240, v76
	s_waitcnt lgkmcnt(3)
	v_mfma_f32_32x32x16_bf16 v[50:65], v[212:215], v[82:85], v[50:65]
	ds_read_b128 v[212:215], v223 offset:51232
	v_add_f32_e32 v241, v241, v77
	v_add_f32_e32 v238, v238, v78
	v_add_f32_e32 v239, v239, v79
	s_waitcnt lgkmcnt(3)
	v_mfma_f32_32x32x16_bf16 v[34:49], v[218:221], v[82:85], v[34:49]
	ds_read_b128 v[218:221], v223 offset:55840
	v_add_f32_e32 v240, v240, v80
	v_add_f32_e32 v241, v241, v81
	v_cvt_pk_bf16_f32 v74, v74, v75
	s_waitcnt lgkmcnt(3)
	v_mfma_f32_32x32x16_bf16 v[18:33], v[230:233], v[82:85], v[18:33]
	ds_read_b128 v[230:233], v223 offset:60448
	v_cvt_pk_bf16_f32 v75, v76, v77
	v_cvt_pk_bf16_f32 v76, v78, v79
	v_cvt_pk_bf16_f32 v77, v80, v81
	s_waitcnt lgkmcnt(3)
	v_mfma_f32_32x32x16_bf16 v[2:17], v[234:237], v[82:85], v[2:17]
	ds_read_b128 v[234:237], v223 offset:65056
	v_add_f32_e32 v238, v238, v239
	v_add_f32_e32 v240, v240, v241
	s_waitcnt lgkmcnt(3)
	v_mfma_f32_32x32x16_bf16 v[50:65], v[212:215], v[90:93], v[50:65]
	ds_read_b128 v[212:215], v223 offset:51264
	v_add_f32_e32 v0, v238, v240
	s_waitcnt lgkmcnt(3)
	v_mfma_f32_32x32x16_bf16 v[34:49], v[218:221], v[90:93], v[34:49]
	ds_read_b128 v[218:221], v223 offset:55872
	v_add_f32_e32 v210, v210, v0
	s_waitcnt lgkmcnt(3)
	v_mfma_f32_32x32x16_bf16 v[18:33], v[230:233], v[90:93], v[18:33]
	ds_read_b128 v[230:233], v223 offset:60480
	s_waitcnt lgkmcnt(3)
	v_mfma_f32_32x32x16_bf16 v[2:17], v[234:237], v[90:93], v[2:17]
	ds_read_b128 v[234:237], v223 offset:65088
	s_waitcnt lgkmcnt(3)
	v_mfma_f32_32x32x16_bf16 v[50:65], v[212:215], v[66:69], v[50:65]
	ds_read_b128 v[212:215], v223 offset:51296
	s_waitcnt lgkmcnt(3)
	v_mfma_f32_32x32x16_bf16 v[34:49], v[218:221], v[66:69], v[34:49]
	ds_read_b128 v[218:221], v223 offset:55904
	s_waitcnt lgkmcnt(3)
	v_mfma_f32_32x32x16_bf16 v[18:33], v[230:233], v[66:69], v[18:33]
	ds_read_b128 v[230:233], v223 offset:60512
	s_waitcnt lgkmcnt(3)
	v_mfma_f32_32x32x16_bf16 v[2:17], v[234:237], v[66:69], v[2:17]
	ds_read_b128 v[234:237], v223 offset:65120
	s_waitcnt lgkmcnt(3)
	v_mfma_f32_32x32x16_bf16 v[50:65], v[212:215], v[74:77], v[50:65]
	s_waitcnt lgkmcnt(2)
	v_mfma_f32_32x32x16_bf16 v[34:49], v[218:221], v[74:77], v[34:49]
	s_waitcnt lgkmcnt(1)
	v_mfma_f32_32x32x16_bf16 v[18:33], v[230:233], v[74:77], v[18:33]
	s_waitcnt lgkmcnt(0)
	v_mfma_f32_32x32x16_bf16 v[2:17], v[234:237], v[74:77], v[2:17]
	v_mov_b64_e32 v[82:83], v[98:99]
	v_mov_b64_e32 v[66:67], v[114:115]
	v_mov_b64_e32 v[84:85], v[100:101]
	v_mov_b64_e32 v[86:87], v[102:103]
	v_mov_b64_e32 v[88:89], v[104:105]
	v_mov_b64_e32 v[90:91], v[106:107]
	v_mov_b64_e32 v[92:93], v[108:109]
	v_mov_b64_e32 v[94:95], v[110:111]
	v_mov_b64_e32 v[96:97], v[112:113]
	v_mov_b64_e32 v[68:69], v[116:117]
	v_mov_b64_e32 v[70:71], v[118:119]
	v_mov_b64_e32 v[72:73], v[120:121]
	v_mov_b64_e32 v[74:75], v[122:123]
	v_mov_b64_e32 v[76:77], v[124:125]
	v_mov_b64_e32 v[78:79], v[126:127]
	v_mov_b64_e32 v[80:81], v[128:129]
	s_or_b64 exec, exec, s[30:31]
	s_andn2_b64 vcc, exec, s[26:27]
	s_cbranch_vccz .LBB0_2571

; #define LAS __attribute__((address_space(3)))
; #define MFMA32(a, b, c) __builtin_amdgcn_mfma_f32_32x32x16_bf16((a), (b), (c), 0, 0, 0)
; DI int perm32k(int i) { return (i & 0x13) | ((i & 8) >> 1) | ((i & 4) << 1); }
; DI bf16x8 pack8(const f32x16& x, int s) { u32x4 p; p.x = pk2(x[8 * s], x[8 * s + 1]); p.y = pk2(x[8 * s + 2], x[8 * s + 3]); p.z = pk2(x[8 * s + 4], x[8 * s + 5]); p.w = pk2(x[8 * s + 6], x[8 * s + 7]); return __builtin_bit_cast(bf16x8, p); }
; DI void attn_unit(LAS unsigned char* lds, const bf16_t* __restrict__ Q, const bf16_t* __restrict__ Kg, const bf16_t* __restrict__ VT, bf16_t* __restrict__ MIX, int b, int h, int c0, int nq, int desc) {
;     ...
;       for (int i = 0; i < 16; ++i) { n0[i] = 0.f; n1[i] = 0.f; }
;       const LAS unsigned char* kb2 = lds + (buf ^ 1) * ATT_KB + perm32k(r31) * KROWB + 16 * hh;
;       __builtin_amdgcn_sched_barrier(0);
; #pragma unroll
;       for (int sx = 0; sx < 12; ++sx) { const bf16x8 a0 = *(const LAS bf16x8*)(kb2 + 32 * sx); const bf16x8 a1 = *(const LAS bf16x8*)(kb2 + 32 * KROWB + 32 * sx);
;         n0 = MFMA32(a0, qf[sx], n0); n1 = MFMA32(a1, qf[sx], n1);
; #pragma unroll
;         for (int j = 0; j < 3; ++j) { const int ei = 3 * sx + j; if (ei < 16) s0[ei] = __builtin_amdgcn_exp2f(s0[ei] - mrun); else if (ei < 32) s1[ei - 16] = __builtin_amdgcn_exp2f(s1[ei - 16] - mrun); }
;         __builtin_amdgcn_sched_barrier(0); }
;       float ps = 0.f;
; #pragma unroll
;       for (int i = 0; i < 16; ++i) ps += s0[i] + s1[i];
;       lrun += ps;
;       bf16x8 pf[4]; pf[0] = pack8(s0, 0); pf[1] = pack8(s0, 1); pf[2] = pack8(s1, 0); pf[3] = pack8(s1, 1);
.LBB0_2594:
	s_xor_b32 s0, s71, 1
	s_mulk_i32 s0, 0x6400
	v_add_u32_e32 v95, s0, v81
	ds_read_b128 v[2:5], v95
	ds_read_b128 v[6:9], v95 offset:12800
	ds_read_b128 v[10:13], v95 offset:32
	ds_read_b128 v[236:239], v95 offset:12832
	v_sub_f32_e32 v112, v112, v233
	v_exp_f32_e32 v112, v112
	v_sub_f32_e32 v113, v113, v233
	v_exp_f32_e32 v113, v113
	v_sub_f32_e32 v114, v114, v233
	v_exp_f32_e32 v114, v114
	s_waitcnt lgkmcnt(3)
	v_mfma_f32_32x32x16_bf16 v[128:143], v[2:5], v[82:85], 0
	ds_read_b128 v[2:5], v95 offset:64
	v_sub_f32_e32 v115, v115, v233
	v_exp_f32_e32 v115, v115
	v_sub_f32_e32 v116, v116, v233
	v_exp_f32_e32 v116, v116
	s_waitcnt lgkmcnt(3)
	v_mfma_f32_32x32x16_bf16 v[144:159], v[6:9], v[82:85], 0
	ds_read_b128 v[6:9], v95 offset:12864
	v_sub_f32_e32 v117, v117, v233
	v_exp_f32_e32 v117, v117
	s_waitcnt lgkmcnt(3)
	v_mfma_f32_32x32x16_bf16 v[128:143], v[10:13], v[86:89], v[128:143]
	ds_read_b128 v[10:13], v95 offset:96
	v_sub_f32_e32 v118, v118, v233
	v_exp_f32_e32 v118, v118
	v_sub_f32_e32 v119, v119, v233
	v_exp_f32_e32 v119, v119
	s_waitcnt lgkmcnt(3)
	v_mfma_f32_32x32x16_bf16 v[144:159], v[236:239], v[86:89], v[144:159]
	ds_read_b128 v[236:239], v95 offset:12896
	v_sub_f32_e32 v120, v120, v233
	v_exp_f32_e32 v120, v120
	s_waitcnt lgkmcnt(3)
	v_mfma_f32_32x32x16_bf16 v[128:143], v[2:5], v[90:93], v[128:143]
	ds_read_b128 v[2:5], v95 offset:128
	v_sub_f32_e32 v121, v121, v233
	v_exp_f32_e32 v121, v121
	v_sub_f32_e32 v122, v122, v233
	v_exp_f32_e32 v122, v122
	s_waitcnt lgkmcnt(3)
	v_mfma_f32_32x32x16_bf16 v[144:159], v[6:9], v[90:93], v[144:159]
	ds_read_b128 v[6:9], v95 offset:12928
	v_sub_f32_e32 v123, v123, v233
	v_exp_f32_e32 v123, v123
	v_add_f32_e32 v14, v112, v116
	v_add_f32_e32 v15, v113, v117
	v_add_f32_e32 v240, v114, v118
	s_waitcnt lgkmcnt(3)
	v_mfma_f32_32x32x16_bf16 v[128:143], v[10:13], v[180:183], v[128:143]
	ds_read_b128 v[10:13], v95 offset:160
	v_sub_f32_e32 v124, v124, v233
	v_exp_f32_e32 v124, v124
	v_sub_f32_e32 v125, v125, v233
	v_exp_f32_e32 v125, v125
	s_waitcnt lgkmcnt(3)
	v_mfma_f32_32x32x16_bf16 v[144:159], v[236:239], v[180:183], v[144:159]
	ds_read_b128 v[236:239], v95 offset:12960
	v_sub_f32_e32 v126, v126, v233
	v_exp_f32_e32 v126, v126
	v_add_f32_e32 v241, v115, v119
	v_cvt_pk_bf16_f32 v112, v112, v113
	v_cvt_pk_bf16_f32 v113, v114, v115
	s_waitcnt lgkmcnt(3)
	v_mfma_f32_32x32x16_bf16 v[128:143], v[2:5], v[184:187], v[128:143]
	ds_read_b128 v[2:5], v95 offset:192
	v_sub_f32_e32 v127, v127, v233
	v_exp_f32_e32 v127, v127
	v_sub_f32_e32 v96, v96, v233
	v_exp_f32_e32 v96, v96
	s_waitcnt lgkmcnt(3)
	v_mfma_f32_32x32x16_bf16 v[144:159], v[6:9], v[184:187], v[144:159]
	ds_read_b128 v[6:9], v95 offset:12992
	v_sub_f32_e32 v97, v97, v233
	v_exp_f32_e32 v97, v97
	v_cvt_pk_bf16_f32 v114, v116, v117
	v_cvt_pk_bf16_f32 v115, v118, v119
	s_waitcnt lgkmcnt(3)
	v_mfma_f32_32x32x16_bf16 v[128:143], v[10:13], v[188:191], v[128:143]
	ds_read_b128 v[10:13], v95 offset:224
	v_sub_f32_e32 v98, v98, v233
	v_exp_f32_e32 v98, v98
	v_sub_f32_e32 v99, v99, v233
	v_exp_f32_e32 v99, v99
	s_waitcnt lgkmcnt(3)
	v_mfma_f32_32x32x16_bf16 v[144:159], v[236:239], v[188:191], v[144:159]
	ds_read_b128 v[236:239], v95 offset:13024
	v_sub_f32_e32 v100, v100, v233
	v_exp_f32_e32 v100, v100
	v_add_f32_e32 v14, v14, v120
	v_add_f32_e32 v15, v15, v121
	v_add_f32_e32 v240, v240, v122
	s_waitcnt lgkmcnt(3)
	v_mfma_f32_32x32x16_bf16 v[128:143], v[2:5], v[192:195], v[128:143]
	ds_read_b128 v[2:5], v95 offset:256
	v_sub_f32_e32 v101, v101, v233
	v_exp_f32_e32 v101, v101
	v_sub_f32_e32 v102, v102, v233
	v_exp_f32_e32 v102, v102
	s_waitcnt lgkmcnt(3)
	v_mfma_f32_32x32x16_bf16 v[144:159], v[6:9], v[192:195], v[144:159]
	ds_read_b128 v[6:9], v95 offset:13056
	v_sub_f32_e32 v103, v103, v233
	v_exp_f32_e32 v103, v103
	v_add_f32_e32 v241, v241, v123
	v_add_f32_e32 v14, v14, v124
	v_add_f32_e32 v15, v15, v125
	s_waitcnt lgkmcnt(3)
	v_mfma_f32_32x32x16_bf16 v[128:143], v[10:13], v[196:199], v[128:143]
	ds_read_b128 v[10:13], v95 offset:288
	v_sub_f32_e32 v104, v104, v233
	v_exp_f32_e32 v104, v104
	v_sub_f32_e32 v105, v105, v233
	v_exp_f32_e32 v105, v105
	s_waitcnt lgkmcnt(3)
	v_mfma_f32_32x32x16_bf16 v[144:159], v[236:239], v[196:199], v[144:159]
	ds_read_b128 v[236:239], v95 offset:13088
	v_sub_f32_e32 v106, v106, v233
	v_exp_f32_e32 v106, v106
	v_add_f32_e32 v240, v240, v126
	v_add_f32_e32 v241, v241, v127
	v_cvt_pk_bf16_f32 v120, v120, v121
	s_waitcnt lgkmcnt(3)
; #define LAS __attribute__((address_space(3)))
; #define MFMA32(a, b, c) __builtin_amdgcn_mfma_f32_32x32x16_bf16((a), (b), (c), 0, 0, 0)
; DI bf16x8 pack8(const f32x16& x, int s) { u32x4 p; p.x = pk2(x[8 * s], x[8 * s + 1]); p.y = pk2(x[8 * s + 2], x[8 * s + 3]); p.z = pk2(x[8 * s + 4], x[8 * s + 5]); p.w = pk2(x[8 * s + 6], x[8 * s + 7]); return __builtin_bit_cast(bf16x8, p); }
; DI void attn_unit(LAS unsigned char* lds, const bf16_t* __restrict__ Q, const bf16_t* __restrict__ Kg, const bf16_t* __restrict__ VT, bf16_t* __restrict__ MIX, int b, int h, int c0, int nq, int desc) {
;     ...
;       for (int sx = 0; sx < 12; ++sx) { const bf16x8 a0 = *(const LAS bf16x8*)(kb2 + 32 * sx); const bf16x8 a1 = *(const LAS bf16x8*)(kb2 + 32 * KROWB + 32 * sx);
;         n0 = MFMA32(a0, qf[sx], n0); n1 = MFMA32(a1, qf[sx], n1);
; #pragma unroll
;         for (int j = 0; j < 3; ++j) { const int ei = 3 * sx + j; if (ei < 16) s0[ei] = __builtin_amdgcn_exp2f(s0[ei] - mrun); else if (ei < 32) s1[ei - 16] = __builtin_amdgcn_exp2f(s1[ei - 16] - mrun); }
;         __builtin_amdgcn_sched_barrier(0); }
;       float ps = 0.f;
; #pragma unroll
;       for (int i = 0; i < 16; ++i) ps += s0[i] + s1[i];
;       lrun += ps;
;       bf16x8 pf[4]; pf[0] = pack8(s0, 0); pf[1] = pack8(s0, 1); pf[2] = pack8(s1, 0); pf[3] = pack8(s1, 1);
;       const LAS unsigned char* vb = lds + 2 * ATT_KB + buf * ATT_VB + r31 * HROW + 16 * hh;
; #pragma unroll
;       for (int kk = 0; kk < 4; ++kk)
; #pragma unroll
;         for (int d = 0; d < 4; ++d) { const bf16x8 a = *(const LAS bf16x8*)(vb + d * 32 * HROW + 32 * kk); O[d] = MFMA32(a, pf[kk], O[d]); }
	v_mfma_f32_32x32x16_bf16 v[128:143], v[2:5], v[200:203], v[128:143]
	ds_read_b128 v[2:5], v95 offset:320
	v_sub_f32_e32 v107, v107, v233
	v_exp_f32_e32 v107, v107
	v_sub_f32_e32 v108, v108, v233
	v_exp_f32_e32 v108, v108
	s_waitcnt lgkmcnt(3)
	v_mfma_f32_32x32x16_bf16 v[144:159], v[6:9], v[200:203], v[144:159]
	ds_read_b128 v[6:9], v95 offset:13120
	v_sub_f32_e32 v109, v109, v233
	v_exp_f32_e32 v109, v109
	v_cvt_pk_bf16_f32 v121, v122, v123
	v_cvt_pk_bf16_f32 v122, v124, v125
	v_cvt_pk_bf16_f32 v123, v126, v127
	s_waitcnt lgkmcnt(3)
	v_mfma_f32_32x32x16_bf16 v[128:143], v[10:13], v[204:207], v[128:143]
	ds_read_b128 v[10:13], v95 offset:352
	v_sub_f32_e32 v110, v110, v233
	v_exp_f32_e32 v110, v110
	v_sub_f32_e32 v111, v111, v233
	v_exp_f32_e32 v111, v111
	s_waitcnt lgkmcnt(3)
	v_mfma_f32_32x32x16_bf16 v[144:159], v[236:239], v[204:207], v[144:159]
	ds_read_b128 v[236:239], v95 offset:13152
	v_add_f32_e32 v14, v14, v96
	v_add_f32_e32 v15, v15, v97
	v_add_f32_e32 v240, v240, v98
	s_waitcnt lgkmcnt(3)
	v_mfma_f32_32x32x16_bf16 v[128:143], v[2:5], v[208:211], v[128:143]
	s_mul_i32 s0, s71, 0x4800
	v_add_u32_e32 v95, s0, v231
	ds_read_b128 v[2:5], v95 offset:51200
	v_add_f32_e32 v241, v241, v99
	v_add_f32_e32 v14, v14, v100
	v_add_f32_e32 v15, v15, v101
	s_waitcnt lgkmcnt(3)
	v_mfma_f32_32x32x16_bf16 v[144:159], v[6:9], v[208:211], v[144:159]
	ds_read_b128 v[6:9], v95 offset:55808
	v_add_f32_e32 v240, v240, v102
	v_add_f32_e32 v241, v241, v103
	v_cvt_pk_bf16_f32 v96, v96, v97
	s_waitcnt lgkmcnt(3)
	v_mfma_f32_32x32x16_bf16 v[128:143], v[10:13], v[212:215], v[128:143]
	ds_read_b128 v[10:13], v95 offset:60416
	v_cvt_pk_bf16_f32 v97, v98, v99
	v_cvt_pk_bf16_f32 v98, v100, v101
	v_cvt_pk_bf16_f32 v99, v102, v103
	s_waitcnt lgkmcnt(3)
	v_mfma_f32_32x32x16_bf16 v[144:159], v[236:239], v[212:215], v[144:159]
	ds_read_b128 v[236:239], v95 offset:65024
	v_add_f32_e32 v14, v14, v104
	v_add_f32_e32 v15, v15, v105
	v_add_f32_e32 v240, v240, v106
	s_waitcnt lgkmcnt(3)
	v_mfma_f32_32x32x16_bf16 v[64:79], v[2:5], v[112:115], v[64:79]
	ds_read_b128 v[2:5], v95 offset:51232
	v_add_f32_e32 v241, v241, v107
	v_add_f32_e32 v14, v14, v108
	v_add_f32_e32 v15, v15, v109
	s_waitcnt lgkmcnt(3)
	v_mfma_f32_32x32x16_bf16 v[48:63], v[6:9], v[112:115], v[48:63]
	ds_read_b128 v[6:9], v95 offset:55840
	v_add_f32_e32 v240, v240, v110
	v_add_f32_e32 v241, v241, v111
	v_cvt_pk_bf16_f32 v104, v104, v105
	s_waitcnt lgkmcnt(3)
	v_mfma_f32_32x32x16_bf16 v[32:47], v[10:13], v[112:115], v[32:47]
	ds_read_b128 v[10:13], v95 offset:60448
	v_cvt_pk_bf16_f32 v105, v106, v107
	v_cvt_pk_bf16_f32 v106, v108, v109
	v_cvt_pk_bf16_f32 v107, v110, v111
	s_waitcnt lgkmcnt(3)
	v_mfma_f32_32x32x16_bf16 v[16:31], v[236:239], v[112:115], v[16:31]
	ds_read_b128 v[236:239], v95 offset:65056
	v_add_f32_e32 v14, v14, v15
	v_add_f32_e32 v240, v240, v241
	s_waitcnt lgkmcnt(3)
	v_mfma_f32_32x32x16_bf16 v[64:79], v[2:5], v[120:123], v[64:79]
	ds_read_b128 v[2:5], v95 offset:51264
	v_add_f32_e32 v0, v14, v240
	s_waitcnt lgkmcnt(3)
	v_mfma_f32_32x32x16_bf16 v[48:63], v[6:9], v[120:123], v[48:63]
	ds_read_b128 v[6:9], v95 offset:55872
	v_add_f32_e32 v80, v80, v0
	s_waitcnt lgkmcnt(3)
	v_mfma_f32_32x32x16_bf16 v[32:47], v[10:13], v[120:123], v[32:47]
	ds_read_b128 v[10:13], v95 offset:60480
	s_waitcnt lgkmcnt(3)
	v_mfma_f32_32x32x16_bf16 v[16:31], v[236:239], v[120:123], v[16:31]
	ds_read_b128 v[236:239], v95 offset:65088
	s_waitcnt lgkmcnt(3)
	v_mfma_f32_32x32x16_bf16 v[64:79], v[2:5], v[96:99], v[64:79]
	ds_read_b128 v[2:5], v95 offset:51296
	s_waitcnt lgkmcnt(3)
	v_mfma_f32_32x32x16_bf16 v[48:63], v[6:9], v[96:99], v[48:63]
	ds_read_b128 v[6:9], v95 offset:55904
	s_waitcnt lgkmcnt(3)
	v_mfma_f32_32x32x16_bf16 v[32:47], v[10:13], v[96:99], v[32:47]
	ds_read_b128 v[10:13], v95 offset:60512
	s_waitcnt lgkmcnt(3)
	v_mfma_f32_32x32x16_bf16 v[16:31], v[236:239], v[96:99], v[16:31]
	ds_read_b128 v[236:239], v95 offset:65120
	s_waitcnt lgkmcnt(3)
	v_mfma_f32_32x32x16_bf16 v[64:79], v[2:5], v[104:107], v[64:79]
	s_waitcnt lgkmcnt(2)
	v_mfma_f32_32x32x16_bf16 v[48:63], v[6:9], v[104:107], v[48:63]
	s_waitcnt lgkmcnt(1)
	v_mfma_f32_32x32x16_bf16 v[32:47], v[10:13], v[104:107], v[32:47]
	s_waitcnt lgkmcnt(0)
	v_mfma_f32_32x32x16_bf16 v[16:31], v[236:239], v[104:107], v[16:31]
	s_or_b64 exec, exec, s[6:7]
	s_andn2_b64 vcc, exec, s[26:27]
	s_cbranch_vccz .LBB0_2603
